# modulation GEMV k-loop rewritten: weight loads prefetched one iteration ahead, one v_fmac per term on the original accumulators (was pk_mul/pk_fma/pk_add trees with operand shuffles); leader acquire a
# speedup vs baseline: 1.0118x; 1.0022x over previous
.LBB0_11:
	v_and_b32_e32 v6, 0x3ff, v5
	v_lshlrev_b32_e32 v14, 2, v6
	v_lshl_add_u64 v[6:7], s[82:83], 0, v[14:15]
	v_cmp_gt_u32_e32 vcc, s20, v5
	s_nop 1
	v_cndmask_b32_e32 v7, v7, v3, vcc
	v_cndmask_b32_e32 v6, v6, v2, vcc
	global_load_dword v6, v[6:7], off
	v_add_u32_e32 v7, 0x200, v5
	v_cmp_lt_u32_e32 vcc, s21, v5
	v_mov_b32_e32 v5, v7
	s_or_b64 s[14:15], vcc, s[14:15]
	v_lshl_add_u64 v[2:3], v[2:3], 0, s[8:9]
	s_waitcnt vmcnt(0)
	v_mul_f32_e32 v7, 0xbfb8aa3b, v6
	v_exp_f32_e32 v7, v7
	s_nop 0
	v_add_f32_e32 v7, 1.0, v7
	v_div_scale_f32 v8, s[16:17], v7, v7, v6
	v_rcp_f32_e32 v9, v8
	v_div_scale_f32 v10, vcc, v6, v7, v6
	v_fma_f32 v11, -v8, v9, 1.0
	v_fmac_f32_e32 v9, v11, v9
	v_mul_f32_e32 v11, v10, v9
	v_fma_f32 v12, -v8, v11, v10
	v_fmac_f32_e32 v11, v12, v9
	v_fma_f32 v8, -v8, v11, v10
	v_div_fmas_f32 v8, v8, v9, v11
	v_div_fixup_f32 v6, v8, v7, v6
	ds_write_b32 v4, v6
	v_add_u32_e32 v4, 0x800, v4
	s_andn2_b64 exec, exec, s[14:15]
	s_cbranch_execnz .LBB0_11
	s_or_b64 exec, exec, s[14:15]
	s_mul_hi_i32 s14, s30, 0x2aaaaaab
	s_lshr_b32 s15, s14, 31
	s_ashr_i32 s14, s14, 3
	s_add_i32 s31, s14, s15
	s_mul_i32 s14, s31, 48
	s_sub_i32 s14, s30, s14
	s_lshl_b32 s16, s14, 7
	s_ashr_i32 s17, s16, 31
	s_mul_i32 s19, s31, 0x1800000
	s_lshl_b64 s[14:15], s[16:17], 2
	s_mul_hi_i32 s18, s31, 0x1800000
	s_add_u32 s34, s19, s14
	s_addc_u32 s35, s18, s15
	v_mov_b32_e32 v70, 0
	s_mov_b64 s[18:19], 0
	v_mov_b32_e32 v71, v70
	v_mov_b32_e32 v26, v70
	v_mov_b32_e32 v27, v70
	v_mov_b32_e32 v28, v70
	v_mov_b32_e32 v29, v70
	v_mov_b32_e32 v30, v70
	v_mov_b32_e32 v31, v70
	v_mov_b32_e32 v32, v70
	v_mov_b32_e32 v33, v70
	v_mov_b32_e32 v36, v70
	v_mov_b32_e32 v37, v70
	v_mov_b32_e32 v38, v70
	v_mov_b32_e32 v39, v70
	v_mov_b32_e32 v40, v70
	v_mov_b32_e32 v41, v70
	v_mov_b32_e32 v42, v70
	v_mov_b32_e32 v43, v70
	v_mov_b32_e32 v24, v70
	v_mov_b32_e32 v25, v70
	v_mov_b32_e32 v66, v70
	v_mov_b32_e32 v67, v70
	v_mov_b32_e32 v64, v70
	v_mov_b32_e32 v65, v70
	v_mov_b32_e32 v62, v70
	v_mov_b32_e32 v63, v70
	v_mov_b32_e32 v80, v70
	v_mov_b32_e32 v81, v70
	v_mov_b32_e32 v78, v70
	v_mov_b32_e32 v79, v70
	v_mov_b32_e32 v74, v70
	v_mov_b32_e32 v75, v70
	v_mov_b32_e32 v88, v70
	v_mov_b32_e32 v89, v70
	v_mov_b32_e32 v44, v70
	v_mov_b32_e32 v45, v70
	v_mov_b32_e32 v46, v70
	v_mov_b32_e32 v47, v70
	v_mov_b32_e32 v48, v70
	v_mov_b32_e32 v49, v70
	v_mov_b32_e32 v50, v70
	v_mov_b32_e32 v51, v70
	v_mov_b32_e32 v52, v70
	v_mov_b32_e32 v53, v70
	v_mov_b32_e32 v54, v70
	v_mov_b32_e32 v55, v70
	v_mov_b32_e32 v56, v70
	v_mov_b32_e32 v57, v70
	v_mov_b32_e32 v58, v70
	v_mov_b32_e32 v59, v70
	v_mov_b32_e32 v60, v70
	v_mov_b32_e32 v61, v70
	v_mov_b32_e32 v34, v70
	v_mov_b32_e32 v35, v70
	v_mov_b32_e32 v72, v70
	v_mov_b32_e32 v73, v70
	v_mov_b32_e32 v68, v70
	v_mov_b32_e32 v69, v70
	v_mov_b32_e32 v86, v70
	v_mov_b32_e32 v87, v70
	v_mov_b32_e32 v84, v70
	v_mov_b32_e32 v85, v70
	v_mov_b32_e32 v82, v70
	v_mov_b32_e32 v83, v70
	v_mov_b32_e32 v76, v70
	v_mov_b32_e32 v77, v70
	v_mov_b32_e32 v109, v106
	v_mov_b32_e32 v110, v1
	v_lshl_add_u64 v[22:23], v[18:19], 0, s[34:35]
	v_add_co_u32_e32 v138, vcc, s22, v22
	s_nop 1
	v_addc_co_u32_e32 v139, vcc, -1, v23, vcc
	global_load_dword v120, v[138:139], off offset:-256 nt
	global_load_dword v121, v[138:139], off nt
	v_add_co_u32_e32 v138, vcc, s23, v22
	s_nop 1
	v_addc_co_u32_e32 v139, vcc, -1, v23, vcc
	global_load_dword v122, v[138:139], off offset:-256 nt
	global_load_dword v123, v[138:139], off nt
	v_add_co_u32_e32 v138, vcc, s24, v22
	s_nop 1
	v_addc_co_u32_e32 v139, vcc, -1, v23, vcc
	global_load_dword v124, v[138:139], off offset:-256 nt
	global_load_dword v125, v[138:139], off nt
	v_add_co_u32_e32 v138, vcc, s25, v22
	s_nop 1
	v_addc_co_u32_e32 v139, vcc, -1, v23, vcc
	global_load_dword v126, v[138:139], off offset:-256 nt
	global_load_dword v127, v[138:139], off nt
	v_add_co_u32_e32 v138, vcc, s26, v22
	s_nop 1
	v_addc_co_u32_e32 v139, vcc, -1, v23, vcc
	global_load_dword v128, v[138:139], off offset:-256 nt
	global_load_dword v129, v[138:139], off nt
	v_add_co_u32_e32 v138, vcc, s27, v22
	s_nop 1
	v_addc_co_u32_e32 v139, vcc, -1, v23, vcc
	global_load_dword v130, v[138:139], off offset:-256 nt
	global_load_dword v131, v[138:139], off nt
	v_add_co_u32_e32 v138, vcc, s28, v22
	s_nop 1
	v_addc_co_u32_e32 v139, vcc, -1, v23, vcc
	global_load_dword v132, v[138:139], off offset:-256 nt
	global_load_dword v133, v[138:139], off nt
	global_load_dword v134, v[22:23], off offset:-256 nt
	global_load_dword v135, v[22:23], off nt
	s_waitcnt lgkmcnt(0)
	s_barrier
.LBB0_13:
	v_add_u32_e32 v110, 8, v110
	v_mov_b32_e32 v140, s10
	v_mov_b32_e32 v141, s11
	v_cmp_ge_u32_e64 s[36:37], v110, v99
	v_add_u32_e32 v190, 0x10000, v109
	v_add_u32_e32 v191, 0x20000, v109
	s_waitcnt vmcnt(8)
	v_mov_b32_e32 v174, v120
	v_mov_b32_e32 v175, v121
	v_mov_b32_e32 v176, v122
	v_mov_b32_e32 v177, v123
	v_mov_b32_e32 v178, v124
	v_mov_b32_e32 v179, v125
	v_mov_b32_e32 v180, v126
	v_mov_b32_e32 v181, v127
	v_cndmask_b32_e64 v140, v140, 0, s[36:37]
	v_cndmask_b32_e64 v141, v141, 0, s[36:37]
	v_lshl_add_u64 v[136:137], v[22:23], 0, v[140:141]
	v_add_co_u32_e32 v138, vcc, s22, v136
	s_nop 1
	v_addc_co_u32_e32 v139, vcc, -1, v137, vcc
	global_load_dword v120, v[138:139], off offset:-256 nt
	global_load_dword v121, v[138:139], off nt
	v_add_co_u32_e32 v138, vcc, s23, v136
	s_nop 1
	v_addc_co_u32_e32 v139, vcc, -1, v137, vcc
	global_load_dword v122, v[138:139], off offset:-256 nt
	global_load_dword v123, v[138:139], off nt
	v_add_co_u32_e32 v138, vcc, s24, v136
	s_nop 1
	v_addc_co_u32_e32 v139, vcc, -1, v137, vcc
	global_load_dword v124, v[138:139], off offset:-256 nt
	global_load_dword v125, v[138:139], off nt
	v_add_co_u32_e32 v138, vcc, s25, v136
	s_nop 1
	v_addc_co_u32_e32 v139, vcc, -1, v137, vcc
	global_load_dword v126, v[138:139], off offset:-256 nt
	global_load_dword v127, v[138:139], off nt
	ds_read_b128 v[142:145], v109
	ds_read_b128 v[146:149], v109 offset:4096
	ds_read_b128 v[150:153], v109 offset:8192
	ds_read_b128 v[154:157], v109 offset:12288
	ds_read_b128 v[158:161], v109 offset:16384
	ds_read_b128 v[162:165], v109 offset:20480
	ds_read_b128 v[166:169], v109 offset:24576
	ds_read_b128 v[170:173], v109 offset:28672
	s_waitcnt lgkmcnt(7)
	v_fmac_f32_e32 v88, v142, v174
	v_fmac_f32_e32 v77, v142, v175
	v_fmac_f32_e32 v88, v143, v176
	v_fmac_f32_e32 v77, v143, v177
	v_fmac_f32_e32 v88, v144, v178
	v_fmac_f32_e32 v77, v144, v179
	v_fmac_f32_e32 v88, v145, v180
	v_fmac_f32_e32 v77, v145, v181
	ds_read_b128 v[142:145], v109 offset:32768
	s_waitcnt lgkmcnt(7)
	v_fmac_f32_e32 v75, v146, v174
	v_fmac_f32_e32 v76, v146, v175
	v_fmac_f32_e32 v75, v147, v176
	v_fmac_f32_e32 v76, v147, v177
	v_fmac_f32_e32 v75, v148, v178
	v_fmac_f32_e32 v76, v148, v179
	v_fmac_f32_e32 v75, v149, v180
	v_fmac_f32_e32 v76, v149, v181
	ds_read_b128 v[146:149], v109 offset:36864
	s_waitcnt lgkmcnt(7)
	v_fmac_f32_e32 v74, v150, v174
	v_fmac_f32_e32 v83, v150, v175
	v_fmac_f32_e32 v74, v151, v176
	v_fmac_f32_e32 v83, v151, v177
	v_fmac_f32_e32 v74, v152, v178
	v_fmac_f32_e32 v83, v152, v179
	v_fmac_f32_e32 v74, v153, v180
	v_fmac_f32_e32 v83, v153, v181
	ds_read_b128 v[150:153], v109 offset:40960
	s_waitcnt lgkmcnt(7)
	v_fmac_f32_e32 v79, v154, v174
	v_fmac_f32_e32 v82, v154, v175
	v_fmac_f32_e32 v79, v155, v176
	v_fmac_f32_e32 v82, v155, v177
	v_fmac_f32_e32 v79, v156, v178
	v_fmac_f32_e32 v82, v156, v179
	v_fmac_f32_e32 v79, v157, v180
	v_fmac_f32_e32 v82, v157, v181
	ds_read_b128 v[154:157], v109 offset:45056
	s_waitcnt lgkmcnt(7)
	v_fmac_f32_e32 v78, v158, v174
	v_fmac_f32_e32 v85, v158, v175
	v_fmac_f32_e32 v78, v159, v176
	v_fmac_f32_e32 v85, v159, v177
	v_fmac_f32_e32 v78, v160, v178
	v_fmac_f32_e32 v85, v160, v179
	v_fmac_f32_e32 v78, v161, v180
	v_fmac_f32_e32 v85, v161, v181
	ds_read_b128 v[158:161], v109 offset:49152
	s_waitcnt lgkmcnt(7)
	v_fmac_f32_e32 v81, v162, v174
	v_fmac_f32_e32 v84, v162, v175
	v_fmac_f32_e32 v81, v163, v176
	v_fmac_f32_e32 v84, v163, v177
	v_fmac_f32_e32 v81, v164, v178
	v_fmac_f32_e32 v84, v164, v179
	v_fmac_f32_e32 v81, v165, v180
	v_fmac_f32_e32 v84, v165, v181
	ds_read_b128 v[162:165], v109 offset:53248
	s_waitcnt lgkmcnt(7)
	v_fmac_f32_e32 v80, v166, v174
	v_fmac_f32_e32 v87, v166, v175
	v_fmac_f32_e32 v80, v167, v176
	v_fmac_f32_e32 v87, v167, v177
	v_fmac_f32_e32 v80, v168, v178
	v_fmac_f32_e32 v87, v168, v179
	v_fmac_f32_e32 v80, v169, v180
	v_fmac_f32_e32 v87, v169, v181
	ds_read_b128 v[166:169], v109 offset:57344
	s_waitcnt lgkmcnt(7)
	v_fmac_f32_e32 v63, v170, v174
	v_fmac_f32_e32 v86, v170, v175
	v_fmac_f32_e32 v63, v171, v176
	v_fmac_f32_e32 v86, v171, v177
	v_fmac_f32_e32 v63, v172, v178
	v_fmac_f32_e32 v86, v172, v179
	v_fmac_f32_e32 v63, v173, v180
	v_fmac_f32_e32 v86, v173, v181
	ds_read_b128 v[170:173], v109 offset:61440
	s_waitcnt lgkmcnt(7)
	v_fmac_f32_e32 v62, v142, v174
	v_fmac_f32_e32 v69, v142, v175
	v_fmac_f32_e32 v62, v143, v176
	v_fmac_f32_e32 v69, v143, v177
	v_fmac_f32_e32 v62, v144, v178
	v_fmac_f32_e32 v69, v144, v179
	v_fmac_f32_e32 v62, v145, v180
	v_fmac_f32_e32 v69, v145, v181
	ds_read_b128 v[142:145], v190
	s_waitcnt lgkmcnt(7)
	v_fmac_f32_e32 v65, v146, v174
	v_fmac_f32_e32 v68, v146, v175
	v_fmac_f32_e32 v65, v147, v176
	v_fmac_f32_e32 v68, v147, v177
	v_fmac_f32_e32 v65, v148, v178
	v_fmac_f32_e32 v68, v148, v179
	v_fmac_f32_e32 v65, v149, v180
	v_fmac_f32_e32 v68, v149, v181
	ds_read_b128 v[146:149], v190 offset:4096
	s_waitcnt lgkmcnt(7)
	v_fmac_f32_e32 v64, v150, v174
	v_fmac_f32_e32 v73, v150, v175
	v_fmac_f32_e32 v64, v151, v176
	v_fmac_f32_e32 v73, v151, v177
	v_fmac_f32_e32 v64, v152, v178
	v_fmac_f32_e32 v73, v152, v179
	v_fmac_f32_e32 v64, v153, v180
	v_fmac_f32_e32 v73, v153, v181
	ds_read_b128 v[150:153], v190 offset:8192
	s_waitcnt lgkmcnt(7)
	v_fmac_f32_e32 v67, v154, v174
	v_fmac_f32_e32 v72, v154, v175
	v_fmac_f32_e32 v67, v155, v176
	v_fmac_f32_e32 v72, v155, v177
	v_fmac_f32_e32 v67, v156, v178
	v_fmac_f32_e32 v72, v156, v179
	v_fmac_f32_e32 v67, v157, v180
	v_fmac_f32_e32 v72, v157, v181
	ds_read_b128 v[154:157], v190 offset:12288
	s_waitcnt lgkmcnt(7)
	v_fmac_f32_e32 v66, v158, v174
	v_fmac_f32_e32 v35, v158, v175
	v_fmac_f32_e32 v66, v159, v176
	v_fmac_f32_e32 v35, v159, v177
	v_fmac_f32_e32 v66, v160, v178
	v_fmac_f32_e32 v35, v160, v179
	v_fmac_f32_e32 v66, v161, v180
	v_fmac_f32_e32 v35, v161, v181
	ds_read_b128 v[158:161], v190 offset:16384
	s_waitcnt lgkmcnt(7)
	v_fmac_f32_e32 v25, v162, v174
	v_fmac_f32_e32 v34, v162, v175
	v_fmac_f32_e32 v25, v163, v176
	v_fmac_f32_e32 v34, v163, v177
	v_fmac_f32_e32 v25, v164, v178
	v_fmac_f32_e32 v34, v164, v179
	v_fmac_f32_e32 v25, v165, v180
	v_fmac_f32_e32 v34, v165, v181
	ds_read_b128 v[162:165], v190 offset:20480
	s_waitcnt lgkmcnt(7)
	v_fmac_f32_e32 v24, v166, v174
	v_fmac_f32_e32 v61, v166, v175
	v_fmac_f32_e32 v24, v167, v176
	v_fmac_f32_e32 v61, v167, v177
	v_fmac_f32_e32 v24, v168, v178
	v_fmac_f32_e32 v61, v168, v179
	v_fmac_f32_e32 v24, v169, v180
	v_fmac_f32_e32 v61, v169, v181
	ds_read_b128 v[166:169], v190 offset:24576
	s_waitcnt lgkmcnt(7)
	v_fmac_f32_e32 v43, v170, v174
	v_fmac_f32_e32 v60, v170, v175
	v_fmac_f32_e32 v43, v171, v176
	v_fmac_f32_e32 v60, v171, v177
	v_fmac_f32_e32 v43, v172, v178
	v_fmac_f32_e32 v60, v172, v179
	v_fmac_f32_e32 v43, v173, v180
	v_fmac_f32_e32 v60, v173, v181
	ds_read_b128 v[170:173], v190 offset:28672
	s_waitcnt lgkmcnt(7)
	v_fmac_f32_e32 v42, v142, v174
	v_fmac_f32_e32 v59, v142, v175
	v_fmac_f32_e32 v42, v143, v176
	v_fmac_f32_e32 v59, v143, v177
	v_fmac_f32_e32 v42, v144, v178
	v_fmac_f32_e32 v59, v144, v179
	v_fmac_f32_e32 v42, v145, v180
	v_fmac_f32_e32 v59, v145, v181
	ds_read_b128 v[142:145], v190 offset:32768
	s_waitcnt lgkmcnt(7)
	v_fmac_f32_e32 v41, v146, v174
	v_fmac_f32_e32 v58, v146, v175
	v_fmac_f32_e32 v41, v147, v176
	v_fmac_f32_e32 v58, v147, v177
	v_fmac_f32_e32 v41, v148, v178
	v_fmac_f32_e32 v58, v148, v179
	v_fmac_f32_e32 v41, v149, v180
	v_fmac_f32_e32 v58, v149, v181
	ds_read_b128 v[146:149], v190 offset:36864
	s_waitcnt lgkmcnt(7)
	v_fmac_f32_e32 v40, v150, v174
	v_fmac_f32_e32 v57, v150, v175
	v_fmac_f32_e32 v40, v151, v176
	v_fmac_f32_e32 v57, v151, v177
	v_fmac_f32_e32 v40, v152, v178
	v_fmac_f32_e32 v57, v152, v179
	v_fmac_f32_e32 v40, v153, v180
	v_fmac_f32_e32 v57, v153, v181
	ds_read_b128 v[150:153], v190 offset:40960
	s_waitcnt lgkmcnt(7)
	v_fmac_f32_e32 v39, v154, v174
	v_fmac_f32_e32 v56, v154, v175
	v_fmac_f32_e32 v39, v155, v176
	v_fmac_f32_e32 v56, v155, v177
	v_fmac_f32_e32 v39, v156, v178
	v_fmac_f32_e32 v56, v156, v179
	v_fmac_f32_e32 v39, v157, v180
	v_fmac_f32_e32 v56, v157, v181
	ds_read_b128 v[154:157], v190 offset:45056
	s_waitcnt lgkmcnt(7)
	v_fmac_f32_e32 v38, v158, v174
	v_fmac_f32_e32 v55, v158, v175
	v_fmac_f32_e32 v38, v159, v176
	v_fmac_f32_e32 v55, v159, v177
	v_fmac_f32_e32 v38, v160, v178
	v_fmac_f32_e32 v55, v160, v179
	v_fmac_f32_e32 v38, v161, v180
	v_fmac_f32_e32 v55, v161, v181
	ds_read_b128 v[158:161], v190 offset:49152
	s_waitcnt lgkmcnt(7)
	v_fmac_f32_e32 v37, v162, v174
	v_fmac_f32_e32 v54, v162, v175
	v_fmac_f32_e32 v37, v163, v176
	v_fmac_f32_e32 v54, v163, v177
	v_fmac_f32_e32 v37, v164, v178
	v_fmac_f32_e32 v54, v164, v179
	v_fmac_f32_e32 v37, v165, v180
	v_fmac_f32_e32 v54, v165, v181
	ds_read_b128 v[162:165], v190 offset:53248
	s_waitcnt lgkmcnt(7)
	v_fmac_f32_e32 v36, v166, v174
	v_fmac_f32_e32 v53, v166, v175
	v_fmac_f32_e32 v36, v167, v176
	v_fmac_f32_e32 v53, v167, v177
	v_fmac_f32_e32 v36, v168, v178
	v_fmac_f32_e32 v53, v168, v179
	v_fmac_f32_e32 v36, v169, v180
	v_fmac_f32_e32 v53, v169, v181
	ds_read_b128 v[166:169], v190 offset:57344
	s_waitcnt lgkmcnt(7)
	v_fmac_f32_e32 v33, v170, v174
	v_fmac_f32_e32 v52, v170, v175
	v_fmac_f32_e32 v33, v171, v176
	v_fmac_f32_e32 v52, v171, v177
	v_fmac_f32_e32 v33, v172, v178
	v_fmac_f32_e32 v52, v172, v179
	v_fmac_f32_e32 v33, v173, v180
	v_fmac_f32_e32 v52, v173, v181
	ds_read_b128 v[170:173], v190 offset:61440
	s_waitcnt lgkmcnt(7)
	v_fmac_f32_e32 v32, v142, v174
	v_fmac_f32_e32 v51, v142, v175
	v_fmac_f32_e32 v32, v143, v176
	v_fmac_f32_e32 v51, v143, v177
	v_fmac_f32_e32 v32, v144, v178
	v_fmac_f32_e32 v51, v144, v179
	v_fmac_f32_e32 v32, v145, v180
	v_fmac_f32_e32 v51, v145, v181
	ds_read_b128 v[142:145], v191
	s_waitcnt lgkmcnt(7)
	v_fmac_f32_e32 v31, v146, v174
	v_fmac_f32_e32 v50, v146, v175
	v_fmac_f32_e32 v31, v147, v176
	v_fmac_f32_e32 v50, v147, v177
	v_fmac_f32_e32 v31, v148, v178
	v_fmac_f32_e32 v50, v148, v179
	v_fmac_f32_e32 v31, v149, v180
	v_fmac_f32_e32 v50, v149, v181
	s_waitcnt lgkmcnt(6)
	v_fmac_f32_e32 v30, v150, v174
	v_fmac_f32_e32 v49, v150, v175
	v_fmac_f32_e32 v30, v151, v176
	v_fmac_f32_e32 v49, v151, v177
	v_fmac_f32_e32 v30, v152, v178
	v_fmac_f32_e32 v49, v152, v179
	v_fmac_f32_e32 v30, v153, v180
	v_fmac_f32_e32 v49, v153, v181
	s_waitcnt lgkmcnt(5)
	v_fmac_f32_e32 v29, v154, v174
	v_fmac_f32_e32 v48, v154, v175
	v_fmac_f32_e32 v29, v155, v176
	v_fmac_f32_e32 v48, v155, v177
	v_fmac_f32_e32 v29, v156, v178
	v_fmac_f32_e32 v48, v156, v179
	v_fmac_f32_e32 v29, v157, v180
	v_fmac_f32_e32 v48, v157, v181
	s_waitcnt lgkmcnt(4)
	v_fmac_f32_e32 v28, v158, v174
	v_fmac_f32_e32 v47, v158, v175
	v_fmac_f32_e32 v28, v159, v176
	v_fmac_f32_e32 v47, v159, v177
	v_fmac_f32_e32 v28, v160, v178
	v_fmac_f32_e32 v47, v160, v179
	v_fmac_f32_e32 v28, v161, v180
	v_fmac_f32_e32 v47, v161, v181
	s_waitcnt lgkmcnt(3)
	v_fmac_f32_e32 v27, v162, v174
	v_fmac_f32_e32 v46, v162, v175
	v_fmac_f32_e32 v27, v163, v176
	v_fmac_f32_e32 v46, v163, v177
	v_fmac_f32_e32 v27, v164, v178
	v_fmac_f32_e32 v46, v164, v179
	v_fmac_f32_e32 v27, v165, v180
	v_fmac_f32_e32 v46, v165, v181
	s_waitcnt lgkmcnt(2)
	v_fmac_f32_e32 v26, v166, v174
	v_fmac_f32_e32 v45, v166, v175
	v_fmac_f32_e32 v26, v167, v176
	v_fmac_f32_e32 v45, v167, v177
	v_fmac_f32_e32 v26, v168, v178
	v_fmac_f32_e32 v45, v168, v179
	v_fmac_f32_e32 v26, v169, v180
	v_fmac_f32_e32 v45, v169, v181
	s_waitcnt lgkmcnt(1)
	v_fmac_f32_e32 v71, v170, v174
	v_fmac_f32_e32 v44, v170, v175
	v_fmac_f32_e32 v71, v171, v176
	v_fmac_f32_e32 v44, v171, v177
	v_fmac_f32_e32 v71, v172, v178
	v_fmac_f32_e32 v44, v172, v179
	v_fmac_f32_e32 v71, v173, v180
	v_fmac_f32_e32 v44, v173, v181
	s_waitcnt lgkmcnt(0)
	v_fmac_f32_e32 v70, v142, v174
	v_fmac_f32_e32 v89, v142, v175
	v_fmac_f32_e32 v70, v143, v176
	v_fmac_f32_e32 v89, v143, v177
	v_fmac_f32_e32 v70, v144, v178
	v_fmac_f32_e32 v89, v144, v179
	v_fmac_f32_e32 v70, v145, v180
	v_fmac_f32_e32 v89, v145, v181
	s_waitcnt vmcnt(8)
	v_mov_b32_e32 v182, v128
	v_mov_b32_e32 v183, v129
	v_mov_b32_e32 v184, v130
	v_mov_b32_e32 v185, v131
	v_mov_b32_e32 v186, v132
	v_mov_b32_e32 v187, v133
	v_mov_b32_e32 v188, v134
	v_mov_b32_e32 v189, v135
	v_add_co_u32_e32 v138, vcc, s26, v136
	s_nop 1
	v_addc_co_u32_e32 v139, vcc, -1, v137, vcc
	global_load_dword v128, v[138:139], off offset:-256 nt
	global_load_dword v129, v[138:139], off nt
	v_add_co_u32_e32 v138, vcc, s27, v136
	s_nop 1
	v_addc_co_u32_e32 v139, vcc, -1, v137, vcc
	global_load_dword v130, v[138:139], off offset:-256 nt
	global_load_dword v131, v[138:139], off nt
	v_add_co_u32_e32 v138, vcc, s28, v136
	s_nop 1
	v_addc_co_u32_e32 v139, vcc, -1, v137, vcc
	global_load_dword v132, v[138:139], off offset:-256 nt
	global_load_dword v133, v[138:139], off nt
	global_load_dword v134, v[136:137], off offset:-256 nt
	global_load_dword v135, v[136:137], off nt
	v_cmp_ge_u32_e32 vcc, v110, v99
	v_lshl_add_u64 v[22:23], v[22:23], 0, s[10:11]
	s_or_b64 s[18:19], vcc, s[18:19]
	ds_read_b128 v[142:145], v109 offset:16
	ds_read_b128 v[146:149], v109 offset:4112
	ds_read_b128 v[150:153], v109 offset:8208
	ds_read_b128 v[154:157], v109 offset:12304
	ds_read_b128 v[158:161], v109 offset:16400
	ds_read_b128 v[162:165], v109 offset:20496
	ds_read_b128 v[166:169], v109 offset:24592
	ds_read_b128 v[170:173], v109 offset:28688
	s_waitcnt lgkmcnt(7)
	v_fmac_f32_e32 v88, v142, v182
	v_fmac_f32_e32 v77, v142, v183
	v_fmac_f32_e32 v88, v143, v184
	v_fmac_f32_e32 v77, v143, v185
	v_fmac_f32_e32 v88, v144, v186
	v_fmac_f32_e32 v77, v144, v187
	v_fmac_f32_e32 v88, v145, v188
	v_fmac_f32_e32 v77, v145, v189
	ds_read_b128 v[142:145], v109 offset:32784
	s_waitcnt lgkmcnt(7)
	v_fmac_f32_e32 v75, v146, v182
	v_fmac_f32_e32 v76, v146, v183
	v_fmac_f32_e32 v75, v147, v184
	v_fmac_f32_e32 v76, v147, v185
	v_fmac_f32_e32 v75, v148, v186
	v_fmac_f32_e32 v76, v148, v187
	v_fmac_f32_e32 v75, v149, v188
	v_fmac_f32_e32 v76, v149, v189
	ds_read_b128 v[146:149], v109 offset:36880
	s_waitcnt lgkmcnt(7)
	v_fmac_f32_e32 v74, v150, v182
	v_fmac_f32_e32 v83, v150, v183
	v_fmac_f32_e32 v74, v151, v184
	v_fmac_f32_e32 v83, v151, v185
	v_fmac_f32_e32 v74, v152, v186
	v_fmac_f32_e32 v83, v152, v187
	v_fmac_f32_e32 v74, v153, v188
	v_fmac_f32_e32 v83, v153, v189
	ds_read_b128 v[150:153], v109 offset:40976
	s_waitcnt lgkmcnt(7)
	v_fmac_f32_e32 v79, v154, v182
	v_fmac_f32_e32 v82, v154, v183
	v_fmac_f32_e32 v79, v155, v184
	v_fmac_f32_e32 v82, v155, v185
	v_fmac_f32_e32 v79, v156, v186
	v_fmac_f32_e32 v82, v156, v187
	v_fmac_f32_e32 v79, v157, v188
	v_fmac_f32_e32 v82, v157, v189
	ds_read_b128 v[154:157], v109 offset:45072
	s_waitcnt lgkmcnt(7)
	v_fmac_f32_e32 v78, v158, v182
	v_fmac_f32_e32 v85, v158, v183
	v_fmac_f32_e32 v78, v159, v184
	v_fmac_f32_e32 v85, v159, v185
	v_fmac_f32_e32 v78, v160, v186
	v_fmac_f32_e32 v85, v160, v187
	v_fmac_f32_e32 v78, v161, v188
	v_fmac_f32_e32 v85, v161, v189
	ds_read_b128 v[158:161], v109 offset:49168
	s_waitcnt lgkmcnt(7)
	v_fmac_f32_e32 v81, v162, v182
	v_fmac_f32_e32 v84, v162, v183
	v_fmac_f32_e32 v81, v163, v184
	v_fmac_f32_e32 v84, v163, v185
	v_fmac_f32_e32 v81, v164, v186
	v_fmac_f32_e32 v84, v164, v187
	v_fmac_f32_e32 v81, v165, v188
	v_fmac_f32_e32 v84, v165, v189
	ds_read_b128 v[162:165], v109 offset:53264
	s_waitcnt lgkmcnt(7)
	v_fmac_f32_e32 v80, v166, v182
	v_fmac_f32_e32 v87, v166, v183
	v_fmac_f32_e32 v80, v167, v184
	v_fmac_f32_e32 v87, v167, v185
	v_fmac_f32_e32 v80, v168, v186
	v_fmac_f32_e32 v87, v168, v187
	v_fmac_f32_e32 v80, v169, v188
	v_fmac_f32_e32 v87, v169, v189
	ds_read_b128 v[166:169], v109 offset:57360
	s_waitcnt lgkmcnt(7)
	v_fmac_f32_e32 v63, v170, v182
	v_fmac_f32_e32 v86, v170, v183
	v_fmac_f32_e32 v63, v171, v184
	v_fmac_f32_e32 v86, v171, v185
	v_fmac_f32_e32 v63, v172, v186
	v_fmac_f32_e32 v86, v172, v187
	v_fmac_f32_e32 v63, v173, v188
	v_fmac_f32_e32 v86, v173, v189
	ds_read_b128 v[170:173], v109 offset:61456
	s_waitcnt lgkmcnt(7)
	v_fmac_f32_e32 v62, v142, v182
	v_fmac_f32_e32 v69, v142, v183
	v_fmac_f32_e32 v62, v143, v184
	v_fmac_f32_e32 v69, v143, v185
	v_fmac_f32_e32 v62, v144, v186
	v_fmac_f32_e32 v69, v144, v187
	v_fmac_f32_e32 v62, v145, v188
	v_fmac_f32_e32 v69, v145, v189
	ds_read_b128 v[142:145], v190 offset:16
	s_waitcnt lgkmcnt(7)
	v_fmac_f32_e32 v65, v146, v182
	v_fmac_f32_e32 v68, v146, v183
	v_fmac_f32_e32 v65, v147, v184
	v_fmac_f32_e32 v68, v147, v185
	v_fmac_f32_e32 v65, v148, v186
	v_fmac_f32_e32 v68, v148, v187
	v_fmac_f32_e32 v65, v149, v188
	v_fmac_f32_e32 v68, v149, v189
	ds_read_b128 v[146:149], v190 offset:4112
	s_waitcnt lgkmcnt(7)
	v_fmac_f32_e32 v64, v150, v182
	v_fmac_f32_e32 v73, v150, v183
	v_fmac_f32_e32 v64, v151, v184
	v_fmac_f32_e32 v73, v151, v185
	v_fmac_f32_e32 v64, v152, v186
	v_fmac_f32_e32 v73, v152, v187
	v_fmac_f32_e32 v64, v153, v188
	v_fmac_f32_e32 v73, v153, v189
	ds_read_b128 v[150:153], v190 offset:8208
	s_waitcnt lgkmcnt(7)
	v_fmac_f32_e32 v67, v154, v182
	v_fmac_f32_e32 v72, v154, v183
	v_fmac_f32_e32 v67, v155, v184
	v_fmac_f32_e32 v72, v155, v185
	v_fmac_f32_e32 v67, v156, v186
	v_fmac_f32_e32 v72, v156, v187
	v_fmac_f32_e32 v67, v157, v188
	v_fmac_f32_e32 v72, v157, v189
	ds_read_b128 v[154:157], v190 offset:12304
	s_waitcnt lgkmcnt(7)
	v_fmac_f32_e32 v66, v158, v182
	v_fmac_f32_e32 v35, v158, v183
	v_fmac_f32_e32 v66, v159, v184
	v_fmac_f32_e32 v35, v159, v185
	v_fmac_f32_e32 v66, v160, v186
	v_fmac_f32_e32 v35, v160, v187
	v_fmac_f32_e32 v66, v161, v188
	v_fmac_f32_e32 v35, v161, v189
	ds_read_b128 v[158:161], v190 offset:16400
	s_waitcnt lgkmcnt(7)
	v_fmac_f32_e32 v25, v162, v182
	v_fmac_f32_e32 v34, v162, v183
	v_fmac_f32_e32 v25, v163, v184
	v_fmac_f32_e32 v34, v163, v185
	v_fmac_f32_e32 v25, v164, v186
	v_fmac_f32_e32 v34, v164, v187
	v_fmac_f32_e32 v25, v165, v188
	v_fmac_f32_e32 v34, v165, v189
	ds_read_b128 v[162:165], v190 offset:20496
	s_waitcnt lgkmcnt(7)
	v_fmac_f32_e32 v24, v166, v182
	v_fmac_f32_e32 v61, v166, v183
	v_fmac_f32_e32 v24, v167, v184
	v_fmac_f32_e32 v61, v167, v185
	v_fmac_f32_e32 v24, v168, v186
	v_fmac_f32_e32 v61, v168, v187
	v_fmac_f32_e32 v24, v169, v188
	v_fmac_f32_e32 v61, v169, v189
	ds_read_b128 v[166:169], v190 offset:24592
	s_waitcnt lgkmcnt(7)
	v_fmac_f32_e32 v43, v170, v182
	v_fmac_f32_e32 v60, v170, v183
	v_fmac_f32_e32 v43, v171, v184
	v_fmac_f32_e32 v60, v171, v185
	v_fmac_f32_e32 v43, v172, v186
	v_fmac_f32_e32 v60, v172, v187
	v_fmac_f32_e32 v43, v173, v188
	v_fmac_f32_e32 v60, v173, v189
	ds_read_b128 v[170:173], v190 offset:28688
	s_waitcnt lgkmcnt(7)
	v_fmac_f32_e32 v42, v142, v182
	v_fmac_f32_e32 v59, v142, v183
	v_fmac_f32_e32 v42, v143, v184
	v_fmac_f32_e32 v59, v143, v185
	v_fmac_f32_e32 v42, v144, v186
	v_fmac_f32_e32 v59, v144, v187
	v_fmac_f32_e32 v42, v145, v188
	v_fmac_f32_e32 v59, v145, v189
	ds_read_b128 v[142:145], v190 offset:32784
	s_waitcnt lgkmcnt(7)
	v_fmac_f32_e32 v41, v146, v182
	v_fmac_f32_e32 v58, v146, v183
	v_fmac_f32_e32 v41, v147, v184
	v_fmac_f32_e32 v58, v147, v185
	v_fmac_f32_e32 v41, v148, v186
	v_fmac_f32_e32 v58, v148, v187
	v_fmac_f32_e32 v41, v149, v188
	v_fmac_f32_e32 v58, v149, v189
	ds_read_b128 v[146:149], v190 offset:36880
	s_waitcnt lgkmcnt(7)
	v_fmac_f32_e32 v40, v150, v182
	v_fmac_f32_e32 v57, v150, v183
	v_fmac_f32_e32 v40, v151, v184
	v_fmac_f32_e32 v57, v151, v185
	v_fmac_f32_e32 v40, v152, v186
	v_fmac_f32_e32 v57, v152, v187
	v_fmac_f32_e32 v40, v153, v188
	v_fmac_f32_e32 v57, v153, v189
	ds_read_b128 v[150:153], v190 offset:40976
	s_waitcnt lgkmcnt(7)
	v_fmac_f32_e32 v39, v154, v182
	v_fmac_f32_e32 v56, v154, v183
	v_fmac_f32_e32 v39, v155, v184
	v_fmac_f32_e32 v56, v155, v185
	v_fmac_f32_e32 v39, v156, v186
	v_fmac_f32_e32 v56, v156, v187
	v_fmac_f32_e32 v39, v157, v188
	v_fmac_f32_e32 v56, v157, v189
	ds_read_b128 v[154:157], v190 offset:45072
	s_waitcnt lgkmcnt(7)
	v_fmac_f32_e32 v38, v158, v182
	v_fmac_f32_e32 v55, v158, v183
	v_fmac_f32_e32 v38, v159, v184
	v_fmac_f32_e32 v55, v159, v185
	v_fmac_f32_e32 v38, v160, v186
	v_fmac_f32_e32 v55, v160, v187
	v_fmac_f32_e32 v38, v161, v188
	v_fmac_f32_e32 v55, v161, v189
	ds_read_b128 v[158:161], v190 offset:49168
	s_waitcnt lgkmcnt(7)
	v_fmac_f32_e32 v37, v162, v182
	v_fmac_f32_e32 v54, v162, v183
	v_fmac_f32_e32 v37, v163, v184
	v_fmac_f32_e32 v54, v163, v185
	v_fmac_f32_e32 v37, v164, v186
	v_fmac_f32_e32 v54, v164, v187
	v_fmac_f32_e32 v37, v165, v188
	v_fmac_f32_e32 v54, v165, v189
	ds_read_b128 v[162:165], v190 offset:53264
	s_waitcnt lgkmcnt(7)
	v_fmac_f32_e32 v36, v166, v182
	v_fmac_f32_e32 v53, v166, v183
	v_fmac_f32_e32 v36, v167, v184
	v_fmac_f32_e32 v53, v167, v185
	v_fmac_f32_e32 v36, v168, v186
	v_fmac_f32_e32 v53, v168, v187
	v_fmac_f32_e32 v36, v169, v188
	v_fmac_f32_e32 v53, v169, v189
	ds_read_b128 v[166:169], v190 offset:57360
	s_waitcnt lgkmcnt(7)
	v_fmac_f32_e32 v33, v170, v182
	v_fmac_f32_e32 v52, v170, v183
	v_fmac_f32_e32 v33, v171, v184
	v_fmac_f32_e32 v52, v171, v185
	v_fmac_f32_e32 v33, v172, v186
	v_fmac_f32_e32 v52, v172, v187
	v_fmac_f32_e32 v33, v173, v188
	v_fmac_f32_e32 v52, v173, v189
	ds_read_b128 v[170:173], v190 offset:61456
	s_waitcnt lgkmcnt(7)
	v_fmac_f32_e32 v32, v142, v182
	v_fmac_f32_e32 v51, v142, v183
	v_fmac_f32_e32 v32, v143, v184
	v_fmac_f32_e32 v51, v143, v185
	v_fmac_f32_e32 v32, v144, v186
	v_fmac_f32_e32 v51, v144, v187
	v_fmac_f32_e32 v32, v145, v188
	v_fmac_f32_e32 v51, v145, v189
	ds_read_b128 v[142:145], v191 offset:16
	s_waitcnt lgkmcnt(7)
	v_fmac_f32_e32 v31, v146, v182
	v_fmac_f32_e32 v50, v146, v183
	v_fmac_f32_e32 v31, v147, v184
	v_fmac_f32_e32 v50, v147, v185
	v_fmac_f32_e32 v31, v148, v186
	v_fmac_f32_e32 v50, v148, v187
	v_fmac_f32_e32 v31, v149, v188
	v_fmac_f32_e32 v50, v149, v189
	s_waitcnt lgkmcnt(6)
	v_fmac_f32_e32 v30, v150, v182
	v_fmac_f32_e32 v49, v150, v183
	v_fmac_f32_e32 v30, v151, v184
	v_fmac_f32_e32 v49, v151, v185
	v_fmac_f32_e32 v30, v152, v186
	v_fmac_f32_e32 v49, v152, v187
	v_fmac_f32_e32 v30, v153, v188
	v_fmac_f32_e32 v49, v153, v189
	s_waitcnt lgkmcnt(5)
	v_fmac_f32_e32 v29, v154, v182
	v_fmac_f32_e32 v48, v154, v183
	v_fmac_f32_e32 v29, v155, v184
	v_fmac_f32_e32 v48, v155, v185
	v_fmac_f32_e32 v29, v156, v186
	v_fmac_f32_e32 v48, v156, v187
	v_fmac_f32_e32 v29, v157, v188
	v_fmac_f32_e32 v48, v157, v189
	s_waitcnt lgkmcnt(4)
	v_fmac_f32_e32 v28, v158, v182
	v_fmac_f32_e32 v47, v158, v183
	v_fmac_f32_e32 v28, v159, v184
	v_fmac_f32_e32 v47, v159, v185
	v_fmac_f32_e32 v28, v160, v186
	v_fmac_f32_e32 v47, v160, v187
	v_fmac_f32_e32 v28, v161, v188
	v_fmac_f32_e32 v47, v161, v189
	s_waitcnt lgkmcnt(3)
	v_fmac_f32_e32 v27, v162, v182
	v_fmac_f32_e32 v46, v162, v183
	v_fmac_f32_e32 v27, v163, v184
	v_fmac_f32_e32 v46, v163, v185
	v_fmac_f32_e32 v27, v164, v186
	v_fmac_f32_e32 v46, v164, v187
	v_fmac_f32_e32 v27, v165, v188
	v_fmac_f32_e32 v46, v165, v189
	s_waitcnt lgkmcnt(2)
	v_fmac_f32_e32 v26, v166, v182
	v_fmac_f32_e32 v45, v166, v183
	v_fmac_f32_e32 v26, v167, v184
	v_fmac_f32_e32 v45, v167, v185
	v_fmac_f32_e32 v26, v168, v186
	v_fmac_f32_e32 v45, v168, v187
	v_fmac_f32_e32 v26, v169, v188
	v_fmac_f32_e32 v45, v169, v189
	s_waitcnt lgkmcnt(1)
	v_fmac_f32_e32 v71, v170, v182
	v_fmac_f32_e32 v44, v170, v183
	v_fmac_f32_e32 v71, v171, v184
	v_fmac_f32_e32 v44, v171, v185
	v_fmac_f32_e32 v71, v172, v186
	v_fmac_f32_e32 v44, v172, v187
	v_fmac_f32_e32 v71, v173, v188
	v_fmac_f32_e32 v44, v173, v189
	s_waitcnt lgkmcnt(0)
	v_fmac_f32_e32 v70, v142, v182
	v_fmac_f32_e32 v89, v142, v183
	v_fmac_f32_e32 v70, v143, v184
	v_fmac_f32_e32 v89, v143, v185
	v_fmac_f32_e32 v70, v144, v186
	v_fmac_f32_e32 v89, v144, v187
	v_fmac_f32_e32 v70, v145, v188
	v_fmac_f32_e32 v89, v145, v189
	v_add_u32_e32 v109, 32, v109
	s_andn2_b64 exec, exec, s[18:19]
	s_cbranch_execnz .LBB0_13
	s_waitcnt vmcnt(0)
	s_or_b64 exec, exec, s[18:19]
	s_mul_i32 s17, s31, 0x1800
	s_add_i32 s17, s17, s16
	v_or_b32_e32 v2, s17, v104
	s_mul_i32 s17, s31, 0xc6000
	s_mul_hi_i32 s16, s31, 0xc6000
	s_add_u32 s14, s17, s14
	v_ashrrev_i32_e32 v3, 31, v2
	s_addc_u32 s15, s16, s15
	v_lshl_add_u64 v[2:3], v[2:3], 2, s[86:87]
	v_lshl_add_u64 v[4:5], v[20:21], 0, s[14:15]
	s_mov_b64 s[14:15], 0
	v_mov_b32_e32 v6, v108
	v_mov_b32_e32 v7, v107
	s_barrier
	ds_write2st64_b32 v103, v88, v77 offset1:1
	ds_write2st64_b32 v103, v75, v76 offset0:2 offset1:3
	ds_write2st64_b32 v103, v74, v83 offset0:4 offset1:5
	ds_write2st64_b32 v103, v79, v82 offset0:6 offset1:7
	ds_write2st64_b32 v103, v78, v85 offset0:8 offset1:9
	ds_write2st64_b32 v103, v81, v84 offset0:10 offset1:11
	ds_write2st64_b32 v103, v80, v87 offset0:12 offset1:13
	ds_write2st64_b32 v103, v63, v86 offset0:14 offset1:15
	ds_write2st64_b32 v103, v62, v69 offset0:16 offset1:17
	ds_write2st64_b32 v103, v65, v68 offset0:18 offset1:19
	ds_write2st64_b32 v103, v64, v73 offset0:20 offset1:21
	ds_write2st64_b32 v103, v67, v72 offset0:22 offset1:23
	ds_write2st64_b32 v103, v66, v35 offset0:24 offset1:25
	ds_write2st64_b32 v103, v25, v34 offset0:26 offset1:27
	ds_write2st64_b32 v103, v24, v61 offset0:28 offset1:29
	ds_write2st64_b32 v103, v43, v60 offset0:30 offset1:31
	ds_write2st64_b32 v103, v42, v59 offset0:32 offset1:33
	ds_write2st64_b32 v103, v41, v58 offset0:34 offset1:35
	ds_write2st64_b32 v103, v40, v57 offset0:36 offset1:37
	ds_write2st64_b32 v103, v39, v56 offset0:38 offset1:39
	ds_write2st64_b32 v103, v38, v55 offset0:40 offset1:41
	ds_write2st64_b32 v103, v37, v54 offset0:42 offset1:43
	ds_write2st64_b32 v103, v36, v53 offset0:44 offset1:45
	ds_write2st64_b32 v103, v33, v52 offset0:46 offset1:47
	ds_write2st64_b32 v103, v32, v51 offset0:48 offset1:49
	ds_write2st64_b32 v103, v31, v50 offset0:50 offset1:51
	ds_write2st64_b32 v103, v30, v49 offset0:52 offset1:53
	ds_write2st64_b32 v103, v29, v48 offset0:54 offset1:55
	ds_write2st64_b32 v103, v28, v47 offset0:56 offset1:57
	ds_write2st64_b32 v103, v27, v46 offset0:58 offset1:59
	ds_write2st64_b32 v103, v26, v45 offset0:60 offset1:61
	ds_write2st64_b32 v103, v71, v44 offset0:62 offset1:63
	ds_write2st64_b32 v103, v70, v89 offset0:64 offset1:65
	s_waitcnt lgkmcnt(0)
	s_barrier

.LBB0_101:
	s_or_b64 exec, exec, s[0:1]
	s_add_i32 s0, s24, 0x900
	s_mov_b32 s1, 0
	s_lshl_b64 s[0:1], s[0:1], 2
	s_add_u32 s0, s6, s0
	s_addc_u32 s1, s7, s1
	v_mov_b32_e32 v2, 1
	v_mov_b64_e32 v[0:1], s[0:1]
	s_waitcnt vmcnt(0) lgkmcnt(0)
	flat_atomic_add v[0:1], v2
	buffer_inv sc1
	s_waitcnt vmcnt(0)

.LBB0_154:
	s_or_b64 exec, exec, s[0:1]
	s_add_i32 s0, s24, 0x900
	s_mov_b32 s1, 0
	s_lshl_b64 s[0:1], s[0:1], 2
	s_add_u32 s0, s36, s0
	s_addc_u32 s1, s37, s1
	v_mov_b32_e32 v2, 1
	v_mov_b64_e32 v[0:1], s[0:1]
	s_waitcnt vmcnt(0) lgkmcnt(0)
	flat_atomic_add v[0:1], v2
	buffer_inv sc1
	s_waitcnt vmcnt(0)

.LBB0_156:
	s_or_b64 exec, exec, s[0:1]
	s_add_i32 s68, s6, 0x900
	s_lshl_b64 s[0:1], s[68:69], 2
	s_add_u32 s0, s38, s0
	s_addc_u32 s1, s39, s1
	v_mov_b64_e32 v[2:3], s[0:1]
	s_waitcnt vmcnt(0) lgkmcnt(0)
	flat_atomic_add v[2:3], v213
	buffer_inv sc1
	s_waitcnt vmcnt(0)

.LBB0_399:
	s_or_b64 exec, exec, s[0:1]
	s_add_i32 s68, s6, 0x900
	s_lshl_b64 s[0:1], s[68:69], 2
	s_add_u32 s0, s52, s0
	s_addc_u32 s1, s53, s1
	v_mov_b64_e32 v[2:3], s[0:1]
	s_waitcnt vmcnt(0) lgkmcnt(0)
	flat_atomic_add v[2:3], v213
	buffer_inv sc1
	s_waitcnt vmcnt(0)

.LBB0_716:
	s_or_b64 exec, exec, s[0:1]
	s_add_i32 s68, s6, 0x900
	s_lshl_b64 s[0:1], s[68:69], 2
	s_add_u32 s0, s46, s0
	s_addc_u32 s1, s47, s1
	v_mov_b64_e32 v[2:3], s[0:1]
	s_waitcnt vmcnt(0) lgkmcnt(0)
	flat_atomic_add v[2:3], v213
	buffer_inv sc1
	s_waitcnt vmcnt(0)

.LBB0_773:
	s_or_b64 exec, exec, s[0:1]
	s_add_i32 s68, s6, 0x900
	s_lshl_b64 s[0:1], s[68:69], 2
	s_add_u32 s0, s4, s0
	s_addc_u32 s1, s5, s1
	v_mov_b64_e32 v[2:3], s[0:1]
	s_waitcnt vmcnt(0) lgkmcnt(0)
	flat_atomic_add v[2:3], v213
	buffer_inv sc1
	s_waitcnt vmcnt(0)
